# v20: NA rel-bias table loaded into LDS once per workgroup per phase (first unit only) instead of per unit
# baseline (speedup 1.0000x reference)
.LBB0_274:
	v_mov_b32_e32 v0, v234
	s_bfe_u32 s39, s47, 0x70002
	v_readfirstlane_b32 s2, v0
	s_ashr_i32 s37, s47, 9
	s_bfe_u32 s36, s2, 0x20006
	s_ashr_i32 s2, s2, 3
	v_mov_b32_e32 v1, s2
	s_lshl_b32 s17, s37, 13
	s_lshl_b32 s2, s39, 6
	v_bfi_b32 v4, s73, v1, v0
	s_or_b32 s2, s2, s17
	s_and_b32 s34, s47, 3
	s_waitcnt vmcnt(19)
	v_add_u32_e32 v144, s2, v4
	v_ashrrev_i32_e32 v145, 31, v144
	s_lshl_b32 s38, s34, 8
	s_lshl_b32 s2, s36, 6
	v_lshlrev_b64 v[2:3], 12, v[144:145]
	s_or_b32 s2, s2, s38
	v_bfe_u32 v5, v0, 5, 1
	v_lshl_add_u64 v[2:3], s[18:19], 0, v[2:3]
	s_lshl_b32 s70, s2, 1
	v_lshl_add_u64 v[2:3], v[2:3], 0, s[70:71]
	v_lshlrev_b32_e32 v146, 4, v5
	v_mov_b32_e32 v147, v201
	v_lshl_add_u64 v[2:3], v[2:3], 0, v[146:147]
	global_load_dwordx4 v[96:99], v[2:3], off
	global_load_dwordx4 v[100:103], v[2:3], off offset:32
	global_load_dwordx4 v[104:107], v[2:3], off offset:64
	global_load_dwordx4 v[108:111], v[2:3], off offset:96
	s_movk_i32 s2, 0x744
	s_and_b32 s16, s22, 3
	v_cmp_gt_i32_e32 vcc, s2, v0
	v_readlane_b32 s4, v255, 4
	s_xor_b32 s4, s4, s47
	s_cmp_eq_u32 s4, 0
	s_cbranch_scc1 .Lna_loadbias
	s_and_b32 s4, s4, 3
	s_cmp_eq_u32 s4, 0
	s_cbranch_scc1 .Lna_skipbias
.Lna_loadbias:
	s_and_saveexec_b64 s[2:3], vcc
	s_cbranch_execz .LBB0_282
	v_max_i32_e32 v1, 0x544, v0
	v_sub_u32_e32 v1, v1, v0
	v_add_u32_e32 v1, 0x1ff, v1
	s_movk_i32 s4, 0x1ff
	v_cmp_lt_u32_e32 vcc, s4, v1
	s_mov_b64 s[6:7], -1
	v_mov_b32_e32 v2, v0
	s_and_saveexec_b64 s[4:5], vcc
	s_cbranch_execz .LBB0_279
	s_mulk_i32 s34, 0x1d10
	v_readlane_b32 s0, v255, 32
	v_lshrrev_b32_e32 v1, 9, v1
	s_add_u32 s6, s0, s34
	v_readlane_b32 s0, v255, 33
	v_add_u32_e32 v6, 1, v1
	s_addc_u32 s7, s0, 0
	v_and_b32_e32 v7, 0xfffffe, v6
	v_add_u32_e32 v1, 0x200, v0
	v_readlane_b32 s0, v255, 14
	s_mov_b64 s[34:35], 0
	v_mov_b32_e32 v9, v7
	v_lshl_add_u32 v8, v0, 2, s0
	v_mov_b64_e32 v[2:3], v[0:1]

.Lna_skipbias:
	v_med3_u32 v1, s39, 4, v241
	v_lshlrev_b32_e32 v2, 4, v0
	v_lshlrev_b32_e32 v1, 6, v1
	v_and_b32_e32 v200, 0x70, v2
	v_add_u32_e32 v2, 0xffffff00, v1
	v_ashrrev_i32_e32 v10, 3, v0
	v_add_u32_e32 v1, s17, v2
	v_add_u32_e32 v6, v1, v10
	v_ashrrev_i32_e32 v7, 31, v6
	v_lshlrev_b64 v[6:7], 12, v[6:7]
	v_lshl_add_u64 v[6:7], s[18:19], 0, v[6:7]
	s_lshl_b32 s2, s38, 1
	s_mov_b32 s3, s71
	s_lshl_b32 s6, s37, 10
	v_lshl_add_u64 v[6:7], v[6:7], 0, s[2:3]
	s_or_b32 s2, s6, s38
	v_add_u32_e32 v8, s2, v10
	v_ashrrev_i32_e32 v9, 31, v8
	v_lshlrev_b64 v[8:9], 14, v[8:9]
	v_lshl_add_u64 v[8:9], s[68:69], 0, v[8:9]
	v_mov_b32_e32 v3, v201
	v_lshl_add_u64 v[2:3], v[2:3], 1, v[8:9]
	v_lshl_add_u64 v[2:3], v[2:3], 0, v[200:201]
	v_add_co_u32_e32 v8, vcc, s72, v2
	s_mov_b32 s2, 0x200000
	s_nop 0
	v_addc_co_u32_e32 v9, vcc, 0, v3, vcc
	global_load_dwordx4 v[112:115], v[2:3], off
	global_load_dwordx4 v[116:119], v[8:9], off
	v_add_co_u32_e32 v8, vcc, s2, v2
	s_mov_b32 s2, 0x300000
	s_nop 0
	v_addc_co_u32_e32 v9, vcc, 0, v3, vcc
	v_add_co_u32_e32 v2, vcc, s2, v2
	v_lshl_add_u64 v[6:7], v[6:7], 0, v[200:201]
	s_nop 0
	v_addc_co_u32_e32 v3, vcc, 0, v3, vcc
	global_load_dwordx4 v[132:135], v[8:9], off
	global_load_dwordx4 v[140:143], v[2:3], off
	global_load_dwordx4 v[120:123], v[6:7], off offset:2048
	global_load_dwordx4 v[124:127], v[6:7], off offset:2176
	global_load_dwordx4 v[128:131], v[6:7], off offset:2304
	global_load_dwordx4 v[136:139], v[6:7], off offset:2432
	v_and_b32_e32 v3, 31, v0
	v_and_b32_e32 v2, 19, v0
	v_lshrrev_b32_e32 v0, 1, v0
	v_mul_lo_u32 v6, v10, s24
	v_lshlrev_b32_e32 v7, 1, v3
	s_waitcnt vmcnt(30)
	v_lshlrev_b32_e32 v148, 3, v5
	v_med3_i32 v5, v4, 8, 56
	v_and_b32_e32 v0, 4, v0
	v_add3_u32 v147, v6, v200, 0
	v_and_b32_e32 v6, 8, v7
	v_sub_u32_e32 v5, v148, v5
	v_or3_b32 v2, v2, v6, v0
	v_mul_u32_u24_e32 v149, 0x90, v2
	v_add_u32_e32 v2, 10, v5
	v_cmp_gt_u32_e64 s[52:53], 16, v2
	v_add_u32_e32 v2, 11, v5
	v_cmp_gt_u32_e64 s[54:55], 16, v2
	v_add_u32_e32 v2, 12, v5
	v_cmp_gt_u32_e64 s[56:57], 16, v2
	v_add_u32_e32 v2, 13, v5
	v_cmp_gt_u32_e64 s[58:59], 16, v2
	v_add_u32_e32 v2, 14, v5
	v_cmp_gt_u32_e64 s[60:61], 16, v2
	v_add_u32_e32 v2, 15, v5
	v_cmp_gt_u32_e64 s[62:63], 16, v2
	v_add_u32_e32 v2, 25, v5
	v_add_u32_e32 v6, 41, v5
	v_cmp_gt_u32_e64 s[66:67], 16, v2
	v_add_u32_e32 v2, 26, v5
	v_cmp_gt_u32_e64 s[82:83], 16, v6
	v_add_u32_e32 v6, 42, v5
	s_mov_b64 s[14:15], s[68:69]
	v_cmp_gt_u32_e64 s[68:69], 16, v2
	v_add_u32_e32 v2, 27, v5
	v_cmp_gt_u32_e64 s[84:85], 16, v6
	v_add_u32_e32 v6, 43, v5
	s_mov_b64 s[0:1], s[70:71]
	s_lshr_b32 s2, s47, 2
	v_cmp_gt_u32_e64 s[70:71], 16, v2
	v_add_u32_e32 v2, 28, v5
	v_cmp_gt_u32_e64 s[86:87], 16, v6
	v_add_u32_e32 v6, 44, v5
	s_and_b32 s35, s2, 0x7f
	v_cmp_gt_u32_e64 s[72:73], 16, v2
	v_add_u32_e32 v2, 29, v5
	v_cmp_gt_u32_e64 s[88:89], 16, v6
	v_add_u32_e32 v6, 45, v5
	v_sub_u32_e32 v4, v148, v4
	v_med3_u32 v8, s35, 4, v241
	v_cmp_gt_u32_e64 s[74:75], 16, v2
	v_add_u32_e32 v2, 30, v5
	v_cmp_gt_u32_e64 s[90:91], 16, v6
	v_add_u32_e32 v6, 46, v5
	s_mul_i32 s3, s36, 0x4800
	v_add_u32_e32 v7, 8, v5
	v_add_u32_e32 v4, 15, v4
	v_add_u32_e32 v9, 9, v5
	s_movk_i32 s2, 0x7c
	v_lshlrev_b32_e32 v12, 7, v8
	s_movk_i32 s4, 0xffef
	v_cmp_gt_u32_e64 s[76:77], 16, v2
	v_add_u32_e32 v2, 31, v5
	v_cmp_gt_u32_e64 s[92:93], 16, v6
	v_add_u32_e32 v6, 47, v5
	s_add_i32 s37, s3, 0
	v_mul_lo_u32 v11, v8, s2
	v_cmp_gt_u32_e64 s[2:3], 16, v7
	v_add_u32_e32 v0, 0xfffffe00, v12
	v_cmp_gt_u32_e64 s[48:49], 16, v9
	v_cmp_lt_u32_e64 s[64:65], s4, v7
	v_cmp_gt_u32_e64 s[78:79], 16, v2
	v_and_b32_e32 v2, -16, v7
	s_movk_i32 s4, 0xffe0
	v_cmp_gt_u32_e64 s[94:95], 16, v6
	v_med3_i32 v6, v4, 0, 30
	v_max_i32_e32 v7, -1, v4
	v_max_i32_e32 v9, -2, v4
	v_max_i32_e32 v12, -3, v4
	v_max_i32_e32 v13, -4, v4
	v_max_i32_e32 v14, -5, v4
	v_max_i32_e32 v15, -6, v4
	v_max_i32_e32 v16, -7, v4
	v_max_i32_e32 v17, -16, v4
	v_max_i32_e32 v18, 0xffffffef, v4
	v_max_i32_e32 v19, 0xffffffee, v4
	v_max_i32_e32 v20, 0xffffffed, v4
	v_max_i32_e32 v21, 0xffffffec, v4
	v_max_i32_e32 v22, 0xffffffeb, v4
	v_max_i32_e32 v23, 0xffffffea, v4
	v_max_i32_e32 v24, 0xffffffe9, v4
	v_max_i32_e32 v25, 0xffffffe0, v4
	v_max_i32_e32 v26, 0xffffffdf, v4
	v_max_i32_e32 v27, 0xffffffde, v4
	v_max_i32_e32 v28, 0xffffffdd, v4
	v_max_i32_e32 v29, 0xffffffdc, v4
	v_max_i32_e32 v30, 0xffffffdb, v4
	v_max_i32_e32 v31, 0xffffffda, v4
	v_max_i32_e32 v32, 0xffffffd9, v4
	v_max_i32_e32 v33, 0xffffffd0, v4
	v_max_i32_e32 v34, 0xffffffcf, v4
	v_max_i32_e32 v35, 0xffffffce, v4
	v_max_i32_e32 v36, 0xffffffcd, v4
	v_max_i32_e32 v37, 0xffffffcc, v4
	v_max_i32_e32 v38, 0xffffffcb, v4
	v_max_i32_e32 v39, 0xffffffca, v4
	v_max_i32_e32 v4, 0xffffffc9, v4
	v_cmp_eq_u32_e64 s[80:81], s4, v2
	s_movk_i32 s4, 0xffd0
	v_add_u32_e32 v4, 55, v4
	s_mulk_i32 s36, 0x744
	v_cmp_eq_u32_e64 s[96:97], s4, v2
	v_add_u32_e32 v2, 57, v5
	v_add_u32_e32 v7, 1, v7
	v_add_u32_e32 v9, 2, v9
	v_add_u32_e32 v12, 3, v12
	v_add_u32_e32 v13, 4, v13
	v_add_u32_e32 v14, 5, v14
	v_add_u32_e32 v15, 6, v15
	v_add_u32_e32 v16, 7, v16
	v_add_u32_e32 v17, 16, v17
	v_add_u32_e32 v18, 17, v18
	v_add_u32_e32 v19, 18, v19
	v_add_u32_e32 v20, 19, v20
	v_add_u32_e32 v21, 20, v21
	v_add_u32_e32 v22, 21, v22
	v_add_u32_e32 v23, 22, v23
	v_add_u32_e32 v24, 23, v24
	v_add_u32_e32 v25, 32, v25
	v_add_u32_e32 v26, 33, v26
	v_add_u32_e32 v27, 34, v27
	v_add_u32_e32 v28, 35, v28
	v_add_u32_e32 v29, 36, v29
	v_add_u32_e32 v30, 37, v30
	v_add_u32_e32 v31, 38, v31
	v_add_u32_e32 v32, 39, v32
	v_add_u32_e32 v33, 48, v33
	v_add_u32_e32 v34, 49, v34
	v_add_u32_e32 v35, 50, v35
	v_add_u32_e32 v36, 51, v36
	v_add_u32_e32 v37, 52, v37
	v_add_u32_e32 v38, 53, v38
	v_add_u32_e32 v39, 54, v39
	v_min_u32_e32 v4, 30, v4
	v_add_u32_e32 v11, s36, v11
	s_mulk_i32 s35, 0x7c
	v_cmp_gt_u32_e64 s[40:41], 16, v2
	v_add_u32_e32 v2, 58, v5
	v_min_u32_e32 v7, 30, v7
	v_min_u32_e32 v9, 30, v9
	v_min_u32_e32 v12, 30, v12
	v_min_u32_e32 v13, 30, v13
	v_min_u32_e32 v14, 30, v14
	v_min_u32_e32 v15, 30, v15
	v_min_u32_e32 v16, 30, v16
	v_min_u32_e32 v17, 30, v17
	v_min_u32_e32 v18, 30, v18
	v_min_u32_e32 v19, 30, v19
	v_min_u32_e32 v20, 30, v20
	v_min_u32_e32 v21, 30, v21
	v_min_u32_e32 v22, 30, v22
	v_min_u32_e32 v23, 30, v23
	v_min_u32_e32 v24, 30, v24
	v_min_u32_e32 v25, 30, v25
	v_min_u32_e32 v26, 30, v26
	v_min_u32_e32 v27, 30, v27
	v_min_u32_e32 v28, 30, v28
	v_min_u32_e32 v29, 30, v29
	v_min_u32_e32 v30, 30, v30
	v_min_u32_e32 v31, 30, v31
	v_min_u32_e32 v32, 30, v32
	v_min_u32_e32 v33, 30, v33
	v_min_u32_e32 v34, 30, v34
	v_min_u32_e32 v35, 30, v35
	v_min_u32_e32 v36, 30, v36
	v_min_u32_e32 v37, 30, v37
	v_min_u32_e32 v38, 30, v38
	v_min_u32_e32 v39, 30, v39
	v_lshl_add_u32 v4, v4, 2, v11
	v_lshlrev_b32_e32 v8, 6, v8
	v_cmp_gt_u32_e64 s[38:39], 16, v2
	v_add_u32_e32 v2, 59, v5
	v_lshl_add_u32 v6, v6, 2, v11
	v_lshl_add_u32 v7, v7, 2, v11
	v_lshl_add_u32 v9, v9, 2, v11
	v_lshl_add_u32 v12, v12, 2, v11
	v_lshl_add_u32 v13, v13, 2, v11
	v_lshl_add_u32 v14, v14, 2, v11
	v_lshl_add_u32 v15, v15, 2, v11
	v_lshl_add_u32 v16, v16, 2, v11
	v_lshl_add_u32 v17, v17, 2, v11
	v_lshl_add_u32 v18, v18, 2, v11
	v_lshl_add_u32 v19, v19, 2, v11
	v_lshl_add_u32 v20, v20, 2, v11
	v_lshl_add_u32 v21, v21, 2, v11
	v_lshl_add_u32 v22, v22, 2, v11
	v_lshl_add_u32 v23, v23, 2, v11
	v_lshl_add_u32 v24, v24, 2, v11
	v_lshl_add_u32 v25, v25, 2, v11
	v_lshl_add_u32 v26, v26, 2, v11
	v_lshl_add_u32 v27, v27, 2, v11
	v_lshl_add_u32 v28, v28, 2, v11
	v_lshl_add_u32 v29, v29, 2, v11
	v_lshl_add_u32 v30, v30, 2, v11
	v_lshl_add_u32 v31, v31, 2, v11
	v_lshl_add_u32 v32, v32, 2, v11
	v_lshl_add_u32 v33, v33, 2, v11
	v_lshl_add_u32 v34, v34, 2, v11
	v_lshl_add_u32 v35, v35, 2, v11
	v_lshl_add_u32 v36, v36, 2, v11
	v_lshl_add_u32 v37, v37, 2, v11
	v_lshl_add_u32 v38, v38, 2, v11
	v_lshl_add_u32 v39, v39, 2, v11
	v_subrev_u32_e32 v11, s35, v4
	v_add_u32_e32 v4, 62, v5
	s_lshl_b32 s34, s16, 8
	v_cmp_gt_u32_e64 s[44:45], 16, v2
	v_add_u32_e32 v2, 60, v5
	v_cmp_gt_u32_e64 s[50:51], 16, v4
	v_add_u32_e32 v4, s17, v8
	v_cmp_gt_u32_e64 s[4:5], 16, v2
	v_add_u32_e32 v2, 61, v5
	s_or_b32 s6, s34, s6
	v_add_u32_e32 v4, v10, v4
	s_lshl_b32 s7, s16, 9
	v_cmp_gt_u32_e64 s[42:43], 16, v2
	v_add_u32_e32 v2, s6, v10
	v_add_u32_e32 v4, 0xffffff00, v4
	v_readlane_b32 s6, v254, 49
	v_add_u32_e32 v40, 63, v5
	v_ashrrev_i32_e32 v5, 31, v4
	s_add_u32 s6, s6, s7
	v_readlane_b32 s7, v254, 50
	v_mov_b32_e32 v1, v201
	v_subrev_u32_e32 v32, s35, v32
	v_subrev_u32_e32 v33, s35, v33
	v_subrev_u32_e32 v34, s35, v34
	v_subrev_u32_e32 v35, s35, v35
	v_subrev_u32_e32 v36, s35, v36
	v_subrev_u32_e32 v37, s35, v37
	v_subrev_u32_e32 v38, s35, v38
	v_subrev_u32_e32 v39, s35, v39
	v_lshlrev_b64 v[4:5], 12, v[4:5]
	s_addc_u32 s7, s7, 0
	s_waitcnt vmcnt(29)
	v_mul_u32_u24_e32 v154, 0x90, v3
	v_ashrrev_i32_e32 v3, 31, v2
	v_mov_b32_e32 v46, v201
	v_mov_b32_e32 v47, v201
	v_subrev_u32_e32 v6, s35, v6
	v_subrev_u32_e32 v7, s35, v7
	v_subrev_u32_e32 v9, s35, v9
	v_subrev_u32_e32 v12, s35, v12
	v_subrev_u32_e32 v13, s35, v13
	v_subrev_u32_e32 v14, s35, v14
	v_subrev_u32_e32 v15, s35, v15
	v_subrev_u32_e32 v16, s35, v16
	v_subrev_u32_e32 v17, s35, v17
	v_subrev_u32_e32 v18, s35, v18
	v_subrev_u32_e32 v19, s35, v19
	v_subrev_u32_e32 v20, s35, v20
	v_subrev_u32_e32 v21, s35, v21
	v_subrev_u32_e32 v22, s35, v22
	v_subrev_u32_e32 v23, s35, v23
	v_subrev_u32_e32 v24, s35, v24
	v_subrev_u32_e32 v25, s35, v25
	v_subrev_u32_e32 v26, s35, v26
	v_subrev_u32_e32 v27, s35, v27
	v_subrev_u32_e32 v28, s35, v28
	v_subrev_u32_e32 v29, s35, v29
	v_subrev_u32_e32 v30, s35, v30
	v_subrev_u32_e32 v31, s35, v31
	v_lshl_add_u64 v[150:151], s[6:7], 0, v[4:5]
	v_cmp_gt_u32_e64 s[6:7], 16, v40
	v_add_u32_e32 v178, s23, v32
	v_add_u32_e32 v179, s23, v33
	v_add_u32_e32 v180, s23, v34
	v_add_u32_e32 v181, s23, v35
	v_add_u32_e32 v182, s23, v36
	v_add_u32_e32 v183, s23, v37
	v_add_u32_e32 v184, s23, v38
	v_add_u32_e32 v185, s23, v39
	v_lshlrev_b64 v[2:3], 14, v[2:3]
	v_lshl_add_u64 v[0:1], s[10:11], 0, v[0:1]
	v_mov_b32_e32 v32, v201
	v_mov_b32_e32 v33, v201
	v_mov_b32_e32 v34, v201
	v_mov_b32_e32 v35, v201
	v_mov_b32_e32 v36, v201
	v_mov_b32_e32 v37, v201
	v_mov_b32_e32 v38, v201
	v_mov_b32_e32 v39, v201
	v_mov_b32_e32 v40, v201
	v_mov_b32_e32 v41, v201
	v_mov_b32_e32 v42, v201
	v_mov_b32_e32 v43, v201
	v_mov_b32_e32 v44, v201
	v_mov_b32_e32 v45, v201
	v_mov_b32_e32 v187, 0
	v_mov_b64_e32 v[62:63], v[46:47]
	s_mov_b32 s16, 0
	v_add_u32_e32 v155, s23, v6
	s_waitcnt vmcnt(28)
	v_add_u32_e32 v156, s23, v7
	v_add_u32_e32 v157, s23, v9
	v_add_u32_e32 v158, s23, v12
	v_add_u32_e32 v159, s23, v13
	v_add_u32_e32 v160, s23, v14
	v_add_u32_e32 v161, s23, v15
	v_add_u32_e32 v162, s23, v16
	v_add_u32_e32 v163, s23, v17
	v_add_u32_e32 v164, s23, v18
	v_add_u32_e32 v165, s23, v19
	v_add_u32_e32 v166, s23, v20
	v_add_u32_e32 v167, s23, v21
	v_add_u32_e32 v168, s23, v22
	v_add_u32_e32 v169, s23, v23
	v_add_u32_e32 v170, s23, v24
	v_add_u32_e32 v171, s23, v25
	v_add_u32_e32 v172, s23, v26
	v_add_u32_e32 v173, s23, v27
	v_add_u32_e32 v174, s23, v28
	v_add_u32_e32 v175, s23, v29
	v_add_u32_e32 v176, s23, v30
	v_add_u32_e32 v177, s23, v31
	v_add_u32_e32 v186, s23, v11
	v_lshl_add_u64 v[152:153], v[0:1], 0, v[2:3]
	v_mov_b64_e32 v[60:61], v[44:45]
	v_mov_b64_e32 v[58:59], v[42:43]
	v_mov_b64_e32 v[56:57], v[40:41]
	v_mov_b64_e32 v[54:55], v[38:39]
	v_mov_b64_e32 v[52:53], v[36:37]
	v_mov_b64_e32 v[50:51], v[34:35]
	v_mov_b64_e32 v[48:49], v[32:33]
	v_mov_b32_e32 v188, 0
	v_mov_b32_e32 v64, 0
	v_mov_b32_e32 v65, v187
	v_mov_b32_e32 v66, v187
	v_mov_b32_e32 v67, v187
	v_mov_b32_e32 v68, v187
	v_mov_b32_e32 v69, v187
	v_mov_b32_e32 v70, v187
	v_mov_b32_e32 v71, v187
	v_mov_b32_e32 v72, v187
	v_mov_b32_e32 v73, v187
	v_mov_b32_e32 v74, v187
	v_mov_b32_e32 v75, v187
	v_mov_b32_e32 v76, v187
	v_mov_b32_e32 v77, v187
	v_mov_b32_e32 v78, v187
	v_mov_b32_e32 v79, v187
	s_mov_b32 s36, 0
	s_waitcnt vmcnt(7)
	ds_write_b128 v147, v[112:115] offset:9216
	s_waitcnt vmcnt(6)
	ds_write_b128 v147, v[116:119] offset:27648
	s_waitcnt vmcnt(5)
	ds_write_b128 v147, v[132:135] offset:46080
	s_waitcnt vmcnt(4)
	ds_write_b128 v147, v[140:143] offset:64512
	s_waitcnt vmcnt(3)
	ds_write_b128 v147, v[120:123]
	s_waitcnt vmcnt(2)
	ds_write_b128 v147, v[124:127] offset:18432
	s_waitcnt vmcnt(1)
	ds_write_b128 v147, v[128:131] offset:36864
	s_waitcnt vmcnt(0)
	ds_write_b128 v147, v[136:139] offset:55296
	s_waitcnt lgkmcnt(0)
	s_barrier
	s_branch .LBB0_284
